# stack v62 + attention near chunks (index > 4): gather addresses from one base plus immediate offsets, the 48 per-element index instructions only for chunk index 4
# speedup vs baseline: 1.0099x; 1.0099x over previous
; #define LAS __attribute__((address_space(3)))
; __device__ __forceinline__ f32x4 mfma16(bf16x8 a, bf16x8 b, f32x4 c) { return __builtin_amdgcn_mfma_f32_16x16x32_bf16(a, b, c, 0, 0, 0); }
; __device__ __forceinline__ void lds_barrier() { asm volatile("s_waitcnt lgkmcnt(0)" ::: "memory"); __builtin_amdgcn_s_barrier(); asm volatile("" ::: "memory"); }
; #define ATT_LOAD(jj_) do { const bf16_t* kb_ = zb + (size_t)((c - 8 + (jj_)) * 64 + skey) * ZLD + hp * 128 + spc * 8; \
;         kr[0] = *(const u32x4*)(kb_ + 256); vr[0] = *(const u32x4*)(kb_ + 512); kr[1] = *(const u32x4*)(kb_ + (size_t)32 * ZLD + 256); vr[1] = *(const u32x4*)(kb_ + (size_t)32 * ZLD + 512); } while (0)
; __device__ __forceinline__ void attn_item(const Params& p, int l, int item, LAS unsigned char* lds) {
;     ...
;     for (int jj = jj0; jj <= 8; ++jj) {
;         LAS unsigned char* Kb = lds + (jj & 1) * BUFB; LAS unsigned char* Vb = Kb + KBUF;
;         *(LAS u32x4*)(Kb + skey * KST + spc * 16) = kr[0]; *(LAS u32x4*)(Kb + (skey + 32) * KST + spc * 16) = kr[1];
;         *(LAS u32x4*)(Vb + skey * VST + spc * 16) = vr[0]; *(LAS u32x4*)(Vb + (skey + 32) * VST + spc * 16) = vr[1];
;         if (jj < 8) ATT_LOAD(jj + 1);
;         lds_barrier();
;         f32x4 s[4];
; #pragma unroll
;         for (int kt = 0; kt < 4; ++kt) { const LAS unsigned char* kp = Kb + (kt * 16 + fr) * KST + hh * 128 + fq * 16;
;             s[kt] = mfma16(*(const LAS bf16x8*)kp, qf0, ZERO4); s[kt] = mfma16(*(const LAS bf16x8*)(kp + 64), qf1, s[kt]); }
;         const int base = (8 - jj) * 64 + q0 + fr;
;         float cmax = -1e30f;
; #pragma unroll
;         for (int kt = 0; kt < 4; ++kt)
; #pragma unroll
;             for (int j = 0; j < 4; ++j) { const int dist = base - (kt * 16 + fq * 4 + j); const int idx = (dist < 256 ? dist : 256) + 63;
;                 const float sv = s[kt][j] * (0.125f * LOG2E) + bias_s[hh * 320 + idx]; s[kt][j] = sv; cmax = fmaxf(cmax, sv); }
;         cmax = fmaxf(cmax, __shfl_xor(cmax, 16)); cmax = fmaxf(cmax, __shfl_xor(cmax, 32));
.LBB0_412:
	v_add_u32_e32 v69, s15, v62
	v_add3_u32 v87, v69, v52, v65
	v_add3_u32 v69, v69, v64, v66
	v_add_u32_e32 v71, s14, v67
	s_sub_i32 s14, s14, 64
	v_lshl_add_u32 v104, v71, 2, v63
	s_cmp_lt_u32 s7, 4
	s_cbranch_scc1 .Lattn_far_a
	s_cmp_gt_u32 s7, 4
	s_cbranch_scc1 .Lattn_far_a
	v_add_u32_e32 v88, 0x200, v71
	v_min_i32_e32 v88, 0x100, v88
	v_lshl_add_u32 v88, v88, 2, v63
	v_add_u32_e32 v89, 0x1ff, v71
	v_min_i32_e32 v89, 0x100, v89
	v_lshl_add_u32 v89, v89, 2, v63
	v_add_u32_e32 v90, 0x1fe, v71
	v_min_i32_e32 v90, 0x100, v90
	v_lshl_add_u32 v90, v90, 2, v63
	v_add_u32_e32 v91, 0x1fd, v71
	v_min_i32_e32 v91, 0x100, v91
	v_lshl_add_u32 v91, v91, 2, v63
	v_add_u32_e32 v92, 0x1f0, v71
	v_min_i32_e32 v92, 0x100, v92
	v_lshl_add_u32 v92, v92, 2, v63
	v_add_u32_e32 v93, 0x1ef, v71
	v_min_i32_e32 v93, 0x100, v93
	v_lshl_add_u32 v93, v93, 2, v63
	v_add_u32_e32 v94, 0x1ee, v71
	v_min_i32_e32 v94, 0x100, v94
	v_lshl_add_u32 v94, v94, 2, v63
	v_add_u32_e32 v95, 0x1ed, v71
	v_min_i32_e32 v95, 0x100, v95
	v_lshl_add_u32 v95, v95, 2, v63
	v_add_u32_e32 v96, 0x1e0, v71
	v_min_i32_e32 v96, 0x100, v96
	v_lshl_add_u32 v96, v96, 2, v63
	v_add_u32_e32 v97, 0x1df, v71
	v_min_i32_e32 v97, 0x100, v97
	v_lshl_add_u32 v97, v97, 2, v63
	v_add_u32_e32 v98, 0x1de, v71
	v_min_i32_e32 v98, 0x100, v98
	v_lshl_add_u32 v98, v98, 2, v63
	v_add_u32_e32 v99, 0x1dd, v71
	v_min_i32_e32 v99, 0x100, v99
	v_lshl_add_u32 v99, v99, 2, v63
	v_add_u32_e32 v100, 0x1d0, v71
	v_min_i32_e32 v100, 0x100, v100
	v_lshl_add_u32 v100, v100, 2, v63
	v_add_u32_e32 v101, 0x1cf, v71
	v_min_i32_e32 v101, 0x100, v101
	v_lshl_add_u32 v101, v101, 2, v63
	v_add_u32_e32 v102, 0x1ce, v71
	v_min_i32_e32 v102, 0x100, v102
	v_lshl_add_u32 v102, v102, 2, v63
	v_add_u32_e32 v103, 0x1cd, v71
	v_min_i32_e32 v103, 0x100, v103
	v_lshl_add_u32 v103, v103, 2, v63
.Lattn_far_a:
	s_mov_b64 s[16:17], 0x58000
	v_lshl_add_u64 v[56:57], v[56:57], 0, s[16:17]
	s_waitcnt lgkmcnt(0)
	s_barrier
	s_cmp_lt_u32 s7, 4
	s_cbranch_scc1 .Lattn_far_b
	s_cmp_gt_u32 s7, 4
	s_cbranch_scc1 .Lattn_near_b
	ds_read_b32 v88, v88 offset:252
	ds_read_b32 v89, v89 offset:252
	ds_read_b32 v90, v90 offset:252
	ds_read_b32 v91, v91 offset:252
	ds_read_b32 v92, v92 offset:252
	ds_read_b32 v93, v93 offset:252
	ds_read_b32 v94, v94 offset:252
	ds_read_b32 v95, v95 offset:252
	ds_read_b32 v96, v96 offset:252
	ds_read_b32 v97, v97 offset:252
	ds_read_b32 v98, v98 offset:252
	ds_read_b32 v99, v99 offset:252
	ds_read_b32 v100, v100 offset:252
	ds_read_b32 v101, v101 offset:252
	ds_read_b32 v102, v102 offset:252
	ds_read_b32 v103, v103 offset:252

; __device__ __forceinline__ void attn_item(const Params& p, int l, int item, LAS unsigned char* lds) {
;     ...
;             for (int j = 0; j < 4; ++j) { const int dist = base - (kt * 16 + fq * 4 + j); const int idx = (dist < 256 ? dist : 256) + 63;
;                 const float sv = s[kt][j] * (0.125f * LOG2E) + bias_s[hh * 320 + idx]; s[kt][j] = sv; cmax = fmaxf(cmax, sv); }
.Lattn_near_b:
	ds_read_b32 v88, v104 offset:2300
	ds_read_b32 v89, v104 offset:2296
	ds_read_b32 v90, v104 offset:2292
	ds_read_b32 v91, v104 offset:2288
	ds_read_b32 v92, v104 offset:2236
	ds_read_b32 v93, v104 offset:2232
	ds_read_b32 v94, v104 offset:2228
	ds_read_b32 v95, v104 offset:2224
	ds_read_b32 v96, v104 offset:2172
	ds_read_b32 v97, v104 offset:2168
	ds_read_b32 v98, v104 offset:2164
	ds_read_b32 v99, v104 offset:2160
	ds_read_b32 v100, v104 offset:2108
	ds_read_b32 v101, v104 offset:2104
	ds_read_b32 v102, v104 offset:2100
	ds_read_b32 v103, v104 offset:2096
	s_branch .Lattn_join_b
